# adds s_setprio 1 around the MFMA block of the four 192x128 GEMM loops and partial lgkmcnt waits (B fragments first) in the two 128x128 in-projection loops
# speedup vs baseline: 1.0319x; 1.0034x over previous
; #define G_TILE(kt_, st_) do { const size_t ko_ = (size_t)(kt_) * 1024; unsigned char* d_ = smem + (st_) * 16384; \
;         _Pragma("unroll") for (int s_ = 0; s_ < 8; ++s_) GLDS16(Abase + (size_t)s_ * ksub + ko_ + voff, d_ + s_ * 1024); \
;         _Pragma("unroll") for (int s_ = 0; s_ < 8; ++s_) GLDS16(Bbase + (size_t)s_ * ksub + ko_ + voff, d_ + 8192 + s_ * 1024); } while (0)
; template <int EPI>
; __device__ __forceinline__ void gemm_tile(const Params& p, int l, const u16* __restrict__ A, int lda, const u16* __restrict__ Bt, int K, int m0, int n0, unsigned char* smem) {
;     ...
;     for (int kt = 0; kt < nk; ++kt) {
;         if (((kt + 1) & 3) == wid && kt + 1 < nk) asm volatile("s_waitcnt vmcnt(0)" ::: "memory");
;         __builtin_amdgcn_s_barrier();
;         asm volatile("" ::: "memory");
;         if ((kt & 3) == wid && kt + 4 < nk) G_TILE(kt + 4, stn);
;         const int so = st * 16384;
;         bf16x8 af[4], bv[4];
; #pragma unroll
;         for (int i = 0; i < 4; ++i) af[i] = *(const bf16x8*)(fa + so + i * 1024);
; #pragma unroll
;         for (int j = 0; j < 4; ++j) bv[j] = *(const bf16x8*)(fb + so + j * 1024);
;         __builtin_amdgcn_s_setprio(1);
; #pragma unroll
;         for (int i = 0; i < 4; ++i)
; #pragma unroll
;             for (int j = 0; j < 4; ++j) acc[i][j] = __builtin_amdgcn_mfma_f32_16x16x32_bf16(af[i], bv[j], acc[i][j], 0, 0, 0);
;         __builtin_amdgcn_s_setprio(0);
.Loin_bar:
	s_barrier
	v_add_u32_e32 v88, s0, v75
	v_add_u32_e32 v104, s0, v74
	ds_read_b128 v[92:95], v104 offset:8192
	ds_read_b128 v[96:99], v104 offset:9216
	ds_read_b128 v[100:103], v104 offset:10240
	ds_read_b128 v[104:107], v104 offset:11264
	ds_read_b128 v[76:79], v88
	ds_read_b128 v[80:83], v88 offset:1024
	ds_read_b128 v[84:87], v88 offset:2048
	ds_read_b128 v[88:91], v88 offset:3072
	s_cmp_lt_u32 s36, 28
	s_cbranch_scc0 .Loin_mm
	s_add_i32 s1, s23, s37
	s_mov_b32 m0, s1
	s_add_i32 s1, s1, 0x400
	global_load_lds_dwordx4 v252, s[30:31]
	s_mov_b32 m0, s1
	s_add_i32 s1, s23, s38
	global_load_lds_dwordx4 v253, s[30:31]
	s_mov_b32 m0, s1
	s_add_i32 s1, s1, 0x400
	global_load_lds_dwordx4 v252, s[28:29]
	s_mov_b32 m0, s1
	s_add_u32 s30, s30, 0x400
	global_load_lds_dwordx4 v253, s[28:29]
	s_addc_u32 s31, s31, 0
	s_add_u32 s28, s28, 0x400
	s_addc_u32 s29, s29, 0
	s_add_i32 s23, s23, 0x4000
	s_cmp_eq_u32 s23, 0x14000
	s_cselect_b32 s23, 0, s23
.Loin_mm:
	s_setprio 1
	s_waitcnt lgkmcnt(3)
	v_mfma_f32_16x16x32_bf16 v[62:65], v[76:79], v[92:95], v[62:65]
	v_mfma_f32_16x16x32_bf16 v[58:61], v[76:79], v[96:99], v[58:61]
	v_mfma_f32_16x16x32_bf16 v[54:57], v[76:79], v[100:103], v[54:57]
	v_mfma_f32_16x16x32_bf16 v[50:53], v[76:79], v[104:107], v[50:53]
	s_waitcnt lgkmcnt(2)
	v_mfma_f32_16x16x32_bf16 v[46:49], v[80:83], v[92:95], v[46:49]
	v_mfma_f32_16x16x32_bf16 v[42:45], v[80:83], v[96:99], v[42:45]
	v_mfma_f32_16x16x32_bf16 v[38:41], v[80:83], v[100:103], v[38:41]
	v_mfma_f32_16x16x32_bf16 v[34:37], v[80:83], v[104:107], v[34:37]
	s_waitcnt lgkmcnt(1)
	v_mfma_f32_16x16x32_bf16 v[30:33], v[84:87], v[92:95], v[30:33]
	v_mfma_f32_16x16x32_bf16 v[26:29], v[84:87], v[96:99], v[26:29]
	v_mfma_f32_16x16x32_bf16 v[22:25], v[84:87], v[100:103], v[22:25]
	v_mfma_f32_16x16x32_bf16 v[18:21], v[84:87], v[104:107], v[18:21]
	s_waitcnt lgkmcnt(0)
	v_mfma_f32_16x16x32_bf16 v[14:17], v[88:91], v[92:95], v[14:17]
	v_mfma_f32_16x16x32_bf16 v[10:13], v[88:91], v[96:99], v[10:13]
	v_mfma_f32_16x16x32_bf16 v[6:9], v[88:91], v[100:103], v[6:9]
	v_mfma_f32_16x16x32_bf16 v[2:5], v[88:91], v[104:107], v[2:5]
	s_setprio 0
	s_add_i32 s0, s0, 0x4000
	s_cmp_eq_u32 s0, 0x14000
	s_cselect_b32 s0, 0, s0
	s_add_i32 s36, s36, 1
	s_cmp_lg_u32 s36, 31
	s_cbranch_scc1 .Loin_head
	s_branch .LBB0_277

; template <int EPI>
; __device__ __forceinline__ void gemm_tile3(const Params& p, int l, const u16* __restrict__ A, int lda, const u16* __restrict__ Bt, int K, int m0, int n0, unsigned char* smem) {
;     ...
;         __builtin_amdgcn_sched_barrier(0);
;         asm volatile("s_waitcnt lgkmcnt(5)" : "+v"(bv[0]), "+v"(bv[1]), "+v"(bv[2]), "+v"(bv[3]), "+v"(af[0]));
;         __builtin_amdgcn_sched_barrier(0);
; #pragma unroll
;         for (int j = 0; j < 4; ++j) acc[0][j] = __builtin_amdgcn_mfma_f32_16x16x32_bf16(bv[j], af[0], acc[0][j], 0, 0, 0);
;         __builtin_amdgcn_sched_barrier(0);
;         asm volatile("s_waitcnt lgkmcnt(4)" : "+v"(af[1]));
;         __builtin_amdgcn_sched_barrier(0);
; #pragma unroll
;         for (int j = 0; j < 4; ++j) acc[1][j] = __builtin_amdgcn_mfma_f32_16x16x32_bf16(bv[j], af[1], acc[1][j], 0, 0, 0);
;         __builtin_amdgcn_sched_barrier(0);
;         asm volatile("s_waitcnt lgkmcnt(3)" : "+v"(af[2]));
;         __builtin_amdgcn_sched_barrier(0);
; #pragma unroll
;         for (int j = 0; j < 4; ++j) acc[2][j] = __builtin_amdgcn_mfma_f32_16x16x32_bf16(bv[j], af[2], acc[2][j], 0, 0, 0);
;         __builtin_amdgcn_sched_barrier(0);
;         asm volatile("s_waitcnt lgkmcnt(2)" : "+v"(af[3]));
;         __builtin_amdgcn_sched_barrier(0);
; #pragma unroll
;         for (int j = 0; j < 4; ++j) acc[3][j] = __builtin_amdgcn_mfma_f32_16x16x32_bf16(bv[j], af[3], acc[3][j], 0, 0, 0);
;         __builtin_amdgcn_sched_barrier(0);
;         asm volatile("s_waitcnt lgkmcnt(1)" : "+v"(af[4]));
;         __builtin_amdgcn_sched_barrier(0);
; #pragma unroll
;         for (int j = 0; j < 4; ++j) acc[4][j] = __builtin_amdgcn_mfma_f32_16x16x32_bf16(bv[j], af[4], acc[4][j], 0, 0, 0);
;         __builtin_amdgcn_sched_barrier(0);
;         asm volatile("s_waitcnt lgkmcnt(0)" : "+v"(af[5]));
;         __builtin_amdgcn_sched_barrier(0);
; #pragma unroll
;         for (int j = 0; j < 4; ++j) acc[5][j] = __builtin_amdgcn_mfma_f32_16x16x32_bf16(bv[j], af[5], acc[5][j], 0, 0, 0);
;         st = (st + 1) & 3;
;         stn = (stn + 1) & 3;
.LoA_mm:
	s_setprio 1
	s_waitcnt lgkmcnt(5)
	s_nop 0
	v_mfma_f32_16x16x32_bf16 v[94:97], v[110:113], v[126:129], v[94:97]
	v_mfma_f32_16x16x32_bf16 v[90:93], v[114:117], v[126:129], v[90:93]
	v_mfma_f32_16x16x32_bf16 v[86:89], v[118:121], v[126:129], v[86:89]
	v_mfma_f32_16x16x32_bf16 v[82:85], v[122:125], v[126:129], v[82:85]
	s_waitcnt lgkmcnt(4)
	s_nop 0
	v_mfma_f32_16x16x32_bf16 v[78:81], v[110:113], v[130:133], v[78:81]
	v_mfma_f32_16x16x32_bf16 v[74:77], v[114:117], v[130:133], v[74:77]
	v_mfma_f32_16x16x32_bf16 v[70:73], v[118:121], v[130:133], v[70:73]
	v_mfma_f32_16x16x32_bf16 v[66:69], v[122:125], v[130:133], v[66:69]
	s_waitcnt lgkmcnt(3)
	s_nop 0
	v_mfma_f32_16x16x32_bf16 v[62:65], v[110:113], v[134:137], v[62:65]
	v_mfma_f32_16x16x32_bf16 v[58:61], v[114:117], v[134:137], v[58:61]
	v_mfma_f32_16x16x32_bf16 v[54:57], v[118:121], v[134:137], v[54:57]
	v_mfma_f32_16x16x32_bf16 v[50:53], v[122:125], v[134:137], v[50:53]
	s_waitcnt lgkmcnt(2)
	s_nop 0
	v_mfma_f32_16x16x32_bf16 v[46:49], v[110:113], v[138:141], v[46:49]
	v_mfma_f32_16x16x32_bf16 v[42:45], v[114:117], v[138:141], v[42:45]
	v_mfma_f32_16x16x32_bf16 v[38:41], v[118:121], v[138:141], v[38:41]
	v_mfma_f32_16x16x32_bf16 v[34:37], v[122:125], v[138:141], v[34:37]
	s_waitcnt lgkmcnt(1)
	s_nop 0
	v_mfma_f32_16x16x32_bf16 v[30:33], v[110:113], v[142:145], v[30:33]
	v_mfma_f32_16x16x32_bf16 v[26:29], v[114:117], v[142:145], v[26:29]
	v_mfma_f32_16x16x32_bf16 v[22:25], v[118:121], v[142:145], v[22:25]
	v_mfma_f32_16x16x32_bf16 v[18:21], v[122:125], v[142:145], v[18:21]
	s_waitcnt lgkmcnt(0)
	s_add_i32 s23, s23, 0x5000
	s_add_i32 s37, s37, 1
	v_mfma_f32_16x16x32_bf16 v[14:17], v[110:113], v[146:149], v[14:17]
	s_cmp_eq_u32 s23, 0x14000
	s_cselect_b32 s23, 0, s23
	v_mfma_f32_16x16x32_bf16 v[10:13], v[114:117], v[146:149], v[10:13]
	s_cmp_lg_u32 s37, 32
	v_mfma_f32_16x16x32_bf16 v[6:9], v[118:121], v[146:149], v[6:9]
	v_mfma_f32_16x16x32_bf16 v[2:5], v[122:125], v[146:149], v[2:5]
	s_setprio 0
	s_cbranch_scc1 .LoA_head
	s_branch .LBB0_451

; template <int EPI>
; __device__ __forceinline__ void gemm_tile3(const Params& p, int l, const u16* __restrict__ A, int lda, const u16* __restrict__ Bt, int K, int m0, int n0, unsigned char* smem) {
;     ...
;         __builtin_amdgcn_sched_barrier(0);
;         asm volatile("s_waitcnt lgkmcnt(5)" : "+v"(bv[0]), "+v"(bv[1]), "+v"(bv[2]), "+v"(bv[3]), "+v"(af[0]));
;         __builtin_amdgcn_sched_barrier(0);
; #pragma unroll
;         for (int j = 0; j < 4; ++j) acc[0][j] = __builtin_amdgcn_mfma_f32_16x16x32_bf16(bv[j], af[0], acc[0][j], 0, 0, 0);
;         __builtin_amdgcn_sched_barrier(0);
;         asm volatile("s_waitcnt lgkmcnt(4)" : "+v"(af[1]));
;         __builtin_amdgcn_sched_barrier(0);
; #pragma unroll
;         for (int j = 0; j < 4; ++j) acc[1][j] = __builtin_amdgcn_mfma_f32_16x16x32_bf16(bv[j], af[1], acc[1][j], 0, 0, 0);
;         __builtin_amdgcn_sched_barrier(0);
;         asm volatile("s_waitcnt lgkmcnt(3)" : "+v"(af[2]));
;         __builtin_amdgcn_sched_barrier(0);
; #pragma unroll
;         for (int j = 0; j < 4; ++j) acc[2][j] = __builtin_amdgcn_mfma_f32_16x16x32_bf16(bv[j], af[2], acc[2][j], 0, 0, 0);
;         __builtin_amdgcn_sched_barrier(0);
;         asm volatile("s_waitcnt lgkmcnt(2)" : "+v"(af[3]));
;         __builtin_amdgcn_sched_barrier(0);
; #pragma unroll
;         for (int j = 0; j < 4; ++j) acc[3][j] = __builtin_amdgcn_mfma_f32_16x16x32_bf16(bv[j], af[3], acc[3][j], 0, 0, 0);
;         __builtin_amdgcn_sched_barrier(0);
;         asm volatile("s_waitcnt lgkmcnt(1)" : "+v"(af[4]));
;         __builtin_amdgcn_sched_barrier(0);
; #pragma unroll
;         for (int j = 0; j < 4; ++j) acc[4][j] = __builtin_amdgcn_mfma_f32_16x16x32_bf16(bv[j], af[4], acc[4][j], 0, 0, 0);
;         __builtin_amdgcn_sched_barrier(0);
;         asm volatile("s_waitcnt lgkmcnt(0)" : "+v"(af[5]));
;         __builtin_amdgcn_sched_barrier(0);
; #pragma unroll
;         for (int j = 0; j < 4; ++j) acc[5][j] = __builtin_amdgcn_mfma_f32_16x16x32_bf16(bv[j], af[5], acc[5][j], 0, 0, 0);
;         st = (st + 1) & 3;
;         stn = (stn + 1) & 3;
.Lf1_mm:
	s_setprio 1
	s_waitcnt lgkmcnt(5)
	s_nop 0
	v_mfma_f32_16x16x32_bf16 v[94:97], v[110:113], v[126:129], v[94:97]
	v_mfma_f32_16x16x32_bf16 v[90:93], v[114:117], v[126:129], v[90:93]
	v_mfma_f32_16x16x32_bf16 v[86:89], v[118:121], v[126:129], v[86:89]
	v_mfma_f32_16x16x32_bf16 v[82:85], v[122:125], v[126:129], v[82:85]
	s_waitcnt lgkmcnt(4)
	s_nop 0
	v_mfma_f32_16x16x32_bf16 v[78:81], v[110:113], v[130:133], v[78:81]
	v_mfma_f32_16x16x32_bf16 v[74:77], v[114:117], v[130:133], v[74:77]
	v_mfma_f32_16x16x32_bf16 v[66:69], v[118:121], v[130:133], v[66:69]
	v_mfma_f32_16x16x32_bf16 v[70:73], v[122:125], v[130:133], v[70:73]
	s_waitcnt lgkmcnt(3)
	s_nop 0
	v_mfma_f32_16x16x32_bf16 v[62:65], v[110:113], v[134:137], v[62:65]
	v_mfma_f32_16x16x32_bf16 v[58:61], v[114:117], v[134:137], v[58:61]
	v_mfma_f32_16x16x32_bf16 v[50:53], v[118:121], v[134:137], v[50:53]
	v_mfma_f32_16x16x32_bf16 v[54:57], v[122:125], v[134:137], v[54:57]
	s_waitcnt lgkmcnt(2)
	s_nop 0
	v_mfma_f32_16x16x32_bf16 v[46:49], v[110:113], v[138:141], v[46:49]
	v_mfma_f32_16x16x32_bf16 v[42:45], v[114:117], v[138:141], v[42:45]
	v_mfma_f32_16x16x32_bf16 v[34:37], v[118:121], v[138:141], v[34:37]
	v_mfma_f32_16x16x32_bf16 v[38:41], v[122:125], v[138:141], v[38:41]
	s_waitcnt lgkmcnt(1)
	s_nop 0
	v_mfma_f32_16x16x32_bf16 v[30:33], v[110:113], v[142:145], v[30:33]
	v_mfma_f32_16x16x32_bf16 v[26:29], v[114:117], v[142:145], v[26:29]
	v_mfma_f32_16x16x32_bf16 v[18:21], v[118:121], v[142:145], v[18:21]
	v_mfma_f32_16x16x32_bf16 v[22:25], v[122:125], v[142:145], v[22:25]
	s_waitcnt lgkmcnt(0)
	s_add_i32 s50, s50, 0x5000
	s_add_i32 s16, s16, 1
	v_mfma_f32_16x16x32_bf16 v[14:17], v[110:113], v[146:149], v[14:17]
	s_cmp_eq_u32 s50, 0x14000
	s_cselect_b32 s50, 0, s50
	v_mfma_f32_16x16x32_bf16 v[10:13], v[114:117], v[146:149], v[10:13]
	s_cmp_lg_u32 s16, 31
	v_mfma_f32_16x16x32_bf16 v[6:9], v[118:121], v[146:149], v[6:9]
	v_mfma_f32_16x16x32_bf16 v[2:5], v[122:125], v[146:149], v[2:5]
	s_setprio 0
	s_cbranch_scc1 .Lf1_head
	s_branch .LBB0_892

; template <int EPI>
; __device__ __forceinline__ void gemm_tile3(const Params& p, int l, const u16* __restrict__ A, int lda, const u16* __restrict__ Bt, int K, int m0, int n0, unsigned char* smem) {
;     ...
;         __builtin_amdgcn_sched_barrier(0);
;         asm volatile("s_waitcnt lgkmcnt(5)" : "+v"(bv[0]), "+v"(bv[1]), "+v"(bv[2]), "+v"(bv[3]), "+v"(af[0]));
;         __builtin_amdgcn_sched_barrier(0);
; #pragma unroll
;         for (int j = 0; j < 4; ++j) acc[0][j] = __builtin_amdgcn_mfma_f32_16x16x32_bf16(bv[j], af[0], acc[0][j], 0, 0, 0);
;         __builtin_amdgcn_sched_barrier(0);
;         asm volatile("s_waitcnt lgkmcnt(4)" : "+v"(af[1]));
;         __builtin_amdgcn_sched_barrier(0);
; #pragma unroll
;         for (int j = 0; j < 4; ++j) acc[1][j] = __builtin_amdgcn_mfma_f32_16x16x32_bf16(bv[j], af[1], acc[1][j], 0, 0, 0);
;         __builtin_amdgcn_sched_barrier(0);
;         asm volatile("s_waitcnt lgkmcnt(3)" : "+v"(af[2]));
;         __builtin_amdgcn_sched_barrier(0);
; #pragma unroll
;         for (int j = 0; j < 4; ++j) acc[2][j] = __builtin_amdgcn_mfma_f32_16x16x32_bf16(bv[j], af[2], acc[2][j], 0, 0, 0);
;         __builtin_amdgcn_sched_barrier(0);
;         asm volatile("s_waitcnt lgkmcnt(2)" : "+v"(af[3]));
;         __builtin_amdgcn_sched_barrier(0);
; #pragma unroll
;         for (int j = 0; j < 4; ++j) acc[3][j] = __builtin_amdgcn_mfma_f32_16x16x32_bf16(bv[j], af[3], acc[3][j], 0, 0, 0);
;         __builtin_amdgcn_sched_barrier(0);
;         asm volatile("s_waitcnt lgkmcnt(1)" : "+v"(af[4]));
;         __builtin_amdgcn_sched_barrier(0);
; #pragma unroll
;         for (int j = 0; j < 4; ++j) acc[4][j] = __builtin_amdgcn_mfma_f32_16x16x32_bf16(bv[j], af[4], acc[4][j], 0, 0, 0);
;         __builtin_amdgcn_sched_barrier(0);
;         asm volatile("s_waitcnt lgkmcnt(0)" : "+v"(af[5]));
;         __builtin_amdgcn_sched_barrier(0);
; #pragma unroll
;         for (int j = 0; j < 4; ++j) acc[5][j] = __builtin_amdgcn_mfma_f32_16x16x32_bf16(bv[j], af[5], acc[5][j], 0, 0, 0);
;         st = (st + 1) & 3;
;         stn = (stn + 1) & 3;
.Lf2_mm:
	s_setprio 1
	s_waitcnt lgkmcnt(5)
	s_nop 0
	v_mfma_f32_16x16x32_bf16 v[94:97], v[110:113], v[126:129], v[94:97]
	v_mfma_f32_16x16x32_bf16 v[90:93], v[114:117], v[126:129], v[90:93]
	v_mfma_f32_16x16x32_bf16 v[86:89], v[118:121], v[126:129], v[86:89]
	v_mfma_f32_16x16x32_bf16 v[82:85], v[122:125], v[126:129], v[82:85]
	s_waitcnt lgkmcnt(4)
	s_nop 0
	v_mfma_f32_16x16x32_bf16 v[78:81], v[110:113], v[130:133], v[78:81]
	v_mfma_f32_16x16x32_bf16 v[74:77], v[114:117], v[130:133], v[74:77]
	v_mfma_f32_16x16x32_bf16 v[70:73], v[118:121], v[130:133], v[70:73]
	v_mfma_f32_16x16x32_bf16 v[66:69], v[122:125], v[130:133], v[66:69]
	s_waitcnt lgkmcnt(3)
	s_nop 0
	v_mfma_f32_16x16x32_bf16 v[62:65], v[110:113], v[134:137], v[62:65]
	v_mfma_f32_16x16x32_bf16 v[58:61], v[114:117], v[134:137], v[58:61]
	v_mfma_f32_16x16x32_bf16 v[54:57], v[118:121], v[134:137], v[54:57]
	v_mfma_f32_16x16x32_bf16 v[50:53], v[122:125], v[134:137], v[50:53]
	s_waitcnt lgkmcnt(2)
	s_nop 0
	v_mfma_f32_16x16x32_bf16 v[46:49], v[110:113], v[138:141], v[46:49]
	v_mfma_f32_16x16x32_bf16 v[42:45], v[114:117], v[138:141], v[42:45]
	v_mfma_f32_16x16x32_bf16 v[38:41], v[118:121], v[138:141], v[38:41]
	v_mfma_f32_16x16x32_bf16 v[34:37], v[122:125], v[138:141], v[34:37]
	s_waitcnt lgkmcnt(1)
	s_nop 0
	v_mfma_f32_16x16x32_bf16 v[30:33], v[110:113], v[142:145], v[30:33]
	v_mfma_f32_16x16x32_bf16 v[26:29], v[114:117], v[142:145], v[26:29]
	v_mfma_f32_16x16x32_bf16 v[22:25], v[118:121], v[142:145], v[22:25]
	v_mfma_f32_16x16x32_bf16 v[18:21], v[122:125], v[142:145], v[18:21]
	s_waitcnt lgkmcnt(0)
	s_add_i32 s41, s41, 0x5000
	s_add_i32 s50, s50, 1
	v_mfma_f32_16x16x32_bf16 v[14:17], v[110:113], v[146:149], v[14:17]
	s_cmp_eq_u32 s41, 0x14000
	s_cselect_b32 s41, 0, s41
	v_mfma_f32_16x16x32_bf16 v[10:13], v[114:117], v[146:149], v[10:13]
	s_cmp_lg_u32 s50, 88
	v_mfma_f32_16x16x32_bf16 v[6:9], v[118:121], v[146:149], v[6:9]
	v_mfma_f32_16x16x32_bf16 v[2:5], v[122:125], v[146:149], v[2:5]
	s_setprio 0
	s_cbranch_scc1 .Lf2_head
	s_branch .LBB0_956
